# v_g33 + MLA loop: MFMA-to-VALU hazard gap (s_nop 6) filled with the five pointer increments moved up from the tile-end block
# speedup vs baseline: 1.0076x; 1.0042x over previous
; template <int DK, int MODE> ...
;     ...
;   auto swrite = [&](int buf) {
; #pragma unroll
;     for (int i = 0; i < NKL; ++i) {
;       const int id = tid + 256 * i, row = id / KCH, ch = id % KCH;
;       *(u32x4*)(sK + buf * 64 * LDK + row * LDK + ch * 8) = rk[i];
;     }
; #pragma unroll
;     for (int i = 0; i < 2; ++i) {
;       const int id = tid + 256 * i, row = id >> 3, ch = id & 7;
;       *(u32x4*)(sV + buf * 64 * 72 + row * 72 + ch * 8) = rv[i];
;     }
;     if (MODE == 1) { if (tid < 64) sF[buf * 64 + tid] = Fref - rf; }
;   };
;     ...
;     if (more) swrite(cur ^ 1);
;     if (MODE == 2) { const int done = __all(R == 0.f); if (lane == 0) sFlag[cur * 4 + wave] = done; }
;     __syncthreads();
;     if (MODE == 2) { if (sFlag[cur * 4] & sFlag[cur * 4 + 1] & sFlag[cur * 4 + 2] & sFlag[cur * 4 + 3]) break; }
;   }
.LBB0_525:
	s_xor_b32 s11, s11, 1
	s_mul_i32 s12, s11, 0x3400
	v_add_u32_e32 v0, s12, v217
	s_waitcnt vmcnt(4)
	ds_write_b128 v0, v[88:91]
	v_add_u32_e32 v0, s12, v218
	s_waitcnt vmcnt(3)
	ds_write_b128 v0, v[84:87]
	v_add_u32_e32 v0, s12, v219
	s_lshl_b32 s11, s11, 12
	s_waitcnt vmcnt(2)
	ds_write_b128 v0, v[10:13]
	s_sub_i32 s11, s12, s11
	v_add_u32_e32 v0, s11, v220
	s_waitcnt vmcnt(1)
	ds_write_b128 v0, v[6:9] offset:26624
	s_add_i32 s9, s9, 64
	s_add_i32 s10, s10, 1
	v_add_u32_e32 v0, s11, v221
	s_cmp_eq_u32 s2, s9
	s_waitcnt vmcnt(0)
	ds_write_b128 v0, v[2:5] offset:26624
	s_waitcnt lgkmcnt(0)
	s_barrier
	s_cbranch_scc1 .LBB0_531

; template <int DK, int MODE> ...
;     ...
;         float mx = s0[0];
; #pragma unroll
;         for (int e = 1; e < 16; ++e) mx = fmaxf(mx, s0[e]);
; #pragma unroll
;         for (int e = 0; e < 16; ++e) mx = fmaxf(mx, s1[e]);
;         mx = fmaxf(mx, __shfl_xor(mx, 32));
;         if (__any(mx > m + 8.f)) {
;           const float mnew = fmaxf(m, mx);
;           const float alpha = __builtin_amdgcn_exp2f(m - mnew);
;           m = mnew; lsum *= alpha;
; #pragma unroll
;           for (int e = 0; e < 16; ++e) { o0[e] *= alpha; o1[e] *= alpha; }
;         }
.LBB0_529:
	v_lshl_add_u64 v[162:163], v[162:163], 0, s[34:35]
	v_lshl_add_u64 v[164:165], v[164:165], 0, s[34:35]
	v_lshl_add_u64 v[166:167], v[166:167], 0, s[36:37]
	v_lshl_add_u64 v[168:169], v[168:169], 0, s[36:37]
	v_lshl_add_u64 v[170:171], v[170:171], 0, s[36:37]
	s_nop 1
	v_max_f32_e32 v0, v64, v65
	v_max3_f32 v0, v0, v66, v67
	v_max3_f32 v0, v0, v68, v69
	v_max3_f32 v0, v0, v70, v71
	v_max3_f32 v0, v0, v72, v73
	v_max3_f32 v0, v0, v74, v75
	v_max3_f32 v0, v0, v76, v77
	v_max3_f32 v0, v0, v78, v79
	v_max3_f32 v0, v0, v48, v49
	v_max3_f32 v0, v0, v50, v51
	v_max3_f32 v0, v0, v52, v53
	v_max3_f32 v0, v0, v54, v55
	v_max3_f32 v0, v0, v56, v57
	v_max3_f32 v0, v0, v58, v59
	v_max3_f32 v0, v0, v60, v61
	v_max3_f32 v0, v0, v62, v63
	ds_bpermute_b32 v14, v216, v0
	s_waitcnt lgkmcnt(0)
	v_max_f32_e32 v0, v0, v14
	v_add_f32_e32 v14, 0x41000000, v155
	v_cmp_gt_f32_e32 vcc, v0, v14
	s_cbranch_vccz .LBB0_524
	v_max_f32_e32 v0, v0, v0
	v_max_f32_e32 v14, v155, v155
	v_max_f32_e32 v14, v14, v0
	v_sub_f32_e32 v0, v155, v14
	v_exp_f32_e32 v0, v0
	v_mov_b32_e32 v155, v14
	v_pk_mul_f32 v[30:31], v[30:31], v[0:1] op_sel_hi:[1,0]
	v_pk_mul_f32 v[28:29], v[28:29], v[0:1] op_sel_hi:[1,0]
	v_pk_mul_f32 v[26:27], v[26:27], v[0:1] op_sel_hi:[1,0]
	v_pk_mul_f32 v[24:25], v[24:25], v[0:1] op_sel_hi:[1,0]
	v_pk_mul_f32 v[22:23], v[22:23], v[0:1] op_sel_hi:[1,0]
	v_pk_mul_f32 v[20:21], v[20:21], v[0:1] op_sel_hi:[1,0]
	v_pk_mul_f32 v[18:19], v[18:19], v[0:1] op_sel_hi:[1,0]
	v_pk_mul_f32 v[16:17], v[16:17], v[0:1] op_sel_hi:[1,0]
	v_pk_mul_f32 v[46:47], v[46:47], v[0:1] op_sel_hi:[1,0]
	v_pk_mul_f32 v[44:45], v[44:45], v[0:1] op_sel_hi:[1,0]
	v_pk_mul_f32 v[42:43], v[42:43], v[0:1] op_sel_hi:[1,0]
	v_pk_mul_f32 v[40:41], v[40:41], v[0:1] op_sel_hi:[1,0]
	v_pk_mul_f32 v[38:39], v[38:39], v[0:1] op_sel_hi:[1,0]
	v_pk_mul_f32 v[36:37], v[36:37], v[0:1] op_sel_hi:[1,0]
	v_pk_mul_f32 v[34:35], v[34:35], v[0:1] op_sel_hi:[1,0]
	v_pk_mul_f32 v[32:33], v[32:33], v[0:1] op_sel_hi:[1,0]
	v_mul_f32_e32 v151, v151, v0
	s_branch .LBB0_524
.Lmla_inactive:
	global_load_dwordx4 v[88:91], v[170:171], off
	global_load_dwordx4 v[84:87], v[168:169], off
	global_load_dwordx4 v[10:13], v[166:167], off
	global_load_dwordx4 v[6:9], v[164:165], off
	s_nop 0
	global_load_dwordx4 v[2:5], v[162:163], off
	v_lshl_add_u64 v[162:163], v[162:163], 0, s[34:35]
	v_lshl_add_u64 v[164:165], v[164:165], 0, s[34:35]
	v_lshl_add_u64 v[166:167], v[166:167], 0, s[36:37]
	v_lshl_add_u64 v[168:169], v[168:169], 0, s[36:37]
	v_lshl_add_u64 v[170:171], v[170:171], 0, s[36:37]
	s_branch .LBB0_525
